# v93 + phase-0 order: all WGs transposes first, then half run row-norm before filter MLP and half after (was: half ran row-norm before transposes)
# speedup vs baseline: 1.0080x; 1.0011x over previous
.Lp0_norm_done:
	s_or_b64 exec, exec, s[0:1]
	v_readlane_b32 s0, v255, 63
	s_nop 0
	s_cmp_eq_u32 s0, 3
	s_cbranch_scc0 .LBB0_22
	s_mov_b32 s0, 2
	v_writelane_b32 v255, s0, 63
	s_branch .Lp0_F

.LBB0_298:
	s_andn2_b64 vcc, exec, s[0:1]
	s_cbranch_vccnz .LBB0_22
	v_readlane_b32 s0, v255, 25
	s_cmp_lg_u32 s0, 0
	s_cbranch_scc1 .LBB0_22
	s_bfe_u32 s0, s96, 0x10003
	v_writelane_b32 v255, s0, 63
.Lp0_parts:
	v_mov_b32_e32 v0, v179
	s_nop 0
	v_cmp_gt_i32_e32 vcc, 64, v0
	s_and_saveexec_b64 s[28:29], vcc
	s_cbranch_execz .LBB0_302
	s_waitcnt lgkmcnt(0)
	v_cvt_f32_i32_e32 v1, v0
	s_mov_b32 s0, 0x7f800000
	v_lshl_add_u32 v0, v0, 2, 0
	v_mul_f32_e32 v1, 0x3d000000, v1
	v_mul_f32_e64 v3, |v1|, 0.5
	v_fract_f32_e32 v4, v3
	v_add_f32_e32 v4, v4, v4
	v_cmp_neq_f32_e32 vcc, s0, v3
	v_cmp_gt_f32_e64 s[0:1], |v1|, 1.0
	v_and_b32_e32 v2, 0x7fffffff, v1
	v_cndmask_b32_e32 v3, 0, v4, vcc
	v_cndmask_b32_e64 v3, |v1|, v3, s[0:1]
	v_add_f32_e32 v4, v3, v3
	v_rndne_f32_e32 v4, v4
	v_fmac_f32_e32 v3, -0.5, v4
	v_cvt_i32_f32_e32 v5, v4
	v_mul_f32_e32 v4, v3, v3
	v_fmamk_f32 v6, v4, 0x3e75aa41, v180
	v_fmaak_f32 v6, v4, v6, 0x40234736
	v_fmaak_f32 v6, v4, v6, 0xc0a55e0e
	s_waitcnt vmcnt(0)
	v_mul_f32_e32 v8, v3, v4
	v_mul_f32_e32 v6, v8, v6
	v_fmac_f32_e32 v6, 0x40490fdb, v3
	v_fmamk_f32 v3, v4, 0x3d4be544, v182
	v_fmaak_f32 v3, v4, v3, 0xbfaad1da
	v_fmaak_f32 v3, v4, v3, 0x4081e0d3
	v_fmaak_f32 v3, v4, v3, 0xc09de9e6
	v_fma_f32 v3, v4, v3, 1.0
	v_and_b32_e32 v4, 1, v5
	v_and_b32_e32 v7, 2, v5
	v_cmp_eq_u32_e32 vcc, 0, v4
	v_cmp_eq_u32_e64 s[0:1], 0, v7
	v_lshlrev_b32_e32 v5, 30, v5
	v_cndmask_b32_e64 v4, -v6, v3, vcc
	v_cndmask_b32_e64 v4, -v4, v4, s[0:1]
	s_movk_i32 s0, 0x1f8
	v_cmp_class_f32_e64 s[0:1], v1, s0
	v_and_b32_e32 v5, 0x80000000, v5
	v_xor_b32_e32 v1, v2, v1
	v_cndmask_b32_e32 v3, v3, v6, vcc
	v_xor_b32_e32 v1, v1, v5
	v_xor_b32_e32 v1, v1, v3
	v_cndmask_b32_e64 v4, v226, v4, s[0:1]
	v_cndmask_b32_e64 v1, v226, v1, s[0:1]
	ds_write2st64_b32 v0, v4, v1 offset0:65 offset1:66

.LBB0_380:
	v_readlane_b32 s0, v255, 63
	s_nop 0
	s_cmp_eq_u32 s0, 1
	s_cbranch_scc0 .Lp0_F
	s_mov_b32 s0, 3
	v_writelane_b32 v255, s0, 63
	s_branch .LBB0_444

.LBB0_444:
	s_mov_b64 s[0:1], exec
	v_readlane_b32 s56, v252, 10
	v_readlane_b32 s57, v252, 11
	v_readlane_b32 s58, v252, 12
	v_readlane_b32 s59, v252, 13
	v_readlane_b32 s60, v252, 14
	v_readlane_b32 s61, v252, 15
	v_readlane_b32 s62, v255, 10
	v_readlane_b32 s63, v255, 11
	v_readlane_b32 s64, v255, 6
	v_readlane_b32 s65, v255, 7
	v_readlane_b32 s66, v255, 8
	v_readlane_b32 s67, v255, 9
	v_readlane_b32 s68, v255, 14
	v_readlane_b32 s69, v255, 15
	v_readlane_b32 s70, v255, 12
	v_readlane_b32 s71, v255, 13
	v_readlane_b32 s2, v254, 13
	v_readlane_b32 s3, v254, 14
	v_readlane_b32 s20, v253, 28
	s_load_dword s43, s[74:75], 0x0
	v_lshrrev_b32_e32 v145, 6, v179
	v_and_b32_e32 v144, 63, v179
	v_xor_b32_e32 v160, 16, v225
	v_readfirstlane_b32 s21, v145
	v_xor_b32_e32 v161, 32, v225
	v_lshlrev_b32_e32 v145, 3, v144
	v_lshlrev_b32_e32 v144, 4, v144
	v_lshlrev_b32_e32 v160, 2, v160
	v_lshlrev_b32_e32 v161, 2, v161
	v_mov_b32_e32 v174, 0x3727c5ac
	s_lshl_b32 s21, s21, 2
	s_add_i32 s41, s20, s21
	s_mov_b32 s6, 0x3a800000
	s_cmp_lt_i32 s41, 0x8000
	s_cbranch_scc0 .Lrn_done
	global_load_dwordx4 v[0:3], v144, s[58:59]
	global_load_dwordx4 v[4:7], v144, s[58:59] offset:1024
	global_load_dwordx4 v[8:11], v144, s[58:59] offset:2048
	global_load_dwordx4 v[12:15], v144, s[58:59] offset:3072
	s_lshl_b32 s7, s41, 12
	v_add_u32_e32 v146, s7, v144
	v_add_u32_e32 v147, 0x1000, v146
	v_add_u32_e32 v148, 0x2000, v146
	v_add_u32_e32 v149, 0x3000, v146
	global_load_dwordx4 v[16:19], v146, s[56:57] nt
	global_load_dwordx4 v[20:23], v146, s[56:57] offset:1024 nt
	global_load_dwordx4 v[24:27], v146, s[56:57] offset:2048 nt
	global_load_dwordx4 v[28:31], v146, s[56:57] offset:3072 nt
	global_load_dwordx4 v[32:35], v147, s[56:57] nt
	global_load_dwordx4 v[36:39], v147, s[56:57] offset:1024 nt
	global_load_dwordx4 v[40:43], v147, s[56:57] offset:2048 nt
	global_load_dwordx4 v[44:47], v147, s[56:57] offset:3072 nt
	global_load_dwordx4 v[48:51], v148, s[56:57] nt
	global_load_dwordx4 v[52:55], v148, s[56:57] offset:1024 nt
	global_load_dwordx4 v[56:59], v148, s[56:57] offset:2048 nt
	global_load_dwordx4 v[60:63], v148, s[56:57] offset:3072 nt
	global_load_dwordx4 v[64:67], v149, s[56:57] nt
	global_load_dwordx4 v[68:71], v149, s[56:57] offset:1024 nt
	global_load_dwordx4 v[72:75], v149, s[56:57] offset:2048 nt
	global_load_dwordx4 v[76:79], v149, s[56:57] offset:3072 nt
	s_waitcnt lgkmcnt(0)
	s_lshl_b32 s43, s43, 5
	s_add_i32 s32, s41, s43
	s_cmp_lt_i32 s32, 0x8000
	s_cbranch_scc0 .Lrn_first_nol
	s_lshl_b32 s7, s32, 12
	v_add_u32_e32 v146, s7, v144
	v_add_u32_e32 v147, 0x1000, v146
	v_add_u32_e32 v148, 0x2000, v146
	v_add_u32_e32 v149, 0x3000, v146
	global_load_dwordx4 v[80:83], v146, s[56:57] nt
	global_load_dwordx4 v[84:87], v146, s[56:57] offset:1024 nt
	global_load_dwordx4 v[88:91], v146, s[56:57] offset:2048 nt
	global_load_dwordx4 v[92:95], v146, s[56:57] offset:3072 nt
	global_load_dwordx4 v[96:99], v147, s[56:57] nt
	global_load_dwordx4 v[100:103], v147, s[56:57] offset:1024 nt
	global_load_dwordx4 v[104:107], v147, s[56:57] offset:2048 nt
	global_load_dwordx4 v[108:111], v147, s[56:57] offset:3072 nt
	global_load_dwordx4 v[112:115], v148, s[56:57] nt
	global_load_dwordx4 v[116:119], v148, s[56:57] offset:1024 nt
	global_load_dwordx4 v[120:123], v148, s[56:57] offset:2048 nt
	global_load_dwordx4 v[124:127], v148, s[56:57] offset:3072 nt
	global_load_dwordx4 v[128:131], v149, s[56:57] nt
	global_load_dwordx4 v[132:135], v149, s[56:57] offset:1024 nt
	global_load_dwordx4 v[136:139], v149, s[56:57] offset:2048 nt
	global_load_dwordx4 v[140:143], v149, s[56:57] offset:3072 nt
	s_waitcnt vmcnt(16)
	s_branch .Lrn_comp_A

.Lrn_step_A:
	s_add_i32 s32, s41, s43
	s_cmp_lt_i32 s32, 0x8000
	s_cbranch_scc0 .Lrn_nol_A
	s_lshl_b32 s7, s32, 12
	v_add_u32_e32 v146, s7, v144
	v_add_u32_e32 v147, 0x1000, v146
	v_add_u32_e32 v148, 0x2000, v146
	v_add_u32_e32 v149, 0x3000, v146
	global_load_dwordx4 v[80:83], v146, s[56:57] nt
	global_load_dwordx4 v[84:87], v146, s[56:57] offset:1024 nt
	global_load_dwordx4 v[88:91], v146, s[56:57] offset:2048 nt
	global_load_dwordx4 v[92:95], v146, s[56:57] offset:3072 nt
	global_load_dwordx4 v[96:99], v147, s[56:57] nt
	global_load_dwordx4 v[100:103], v147, s[56:57] offset:1024 nt
	global_load_dwordx4 v[104:107], v147, s[56:57] offset:2048 nt
	global_load_dwordx4 v[108:111], v147, s[56:57] offset:3072 nt
	global_load_dwordx4 v[112:115], v148, s[56:57] nt
	global_load_dwordx4 v[116:119], v148, s[56:57] offset:1024 nt
	global_load_dwordx4 v[120:123], v148, s[56:57] offset:2048 nt
	global_load_dwordx4 v[124:127], v148, s[56:57] offset:3072 nt
	global_load_dwordx4 v[128:131], v149, s[56:57] nt
	global_load_dwordx4 v[132:135], v149, s[56:57] offset:1024 nt
	global_load_dwordx4 v[136:139], v149, s[56:57] offset:2048 nt
	global_load_dwordx4 v[140:143], v149, s[56:57] offset:3072 nt
	s_waitcnt vmcnt(32)
	s_branch .Lrn_comp_A

.Lrn_comp_A:
	v_pk_mul_f32 v[164:165], v[16:17], v[16:17]
	v_pk_mul_f32 v[166:167], v[32:33], v[32:33]
	v_pk_mul_f32 v[168:169], v[48:49], v[48:49]
	v_pk_mul_f32 v[170:171], v[64:65], v[64:65]
	v_pk_fma_f32 v[164:165], v[18:19], v[18:19], v[164:165]
	v_pk_fma_f32 v[166:167], v[34:35], v[34:35], v[166:167]
	v_pk_fma_f32 v[168:169], v[50:51], v[50:51], v[168:169]
	v_pk_fma_f32 v[170:171], v[66:67], v[66:67], v[170:171]
	v_pk_fma_f32 v[164:165], v[20:21], v[20:21], v[164:165]
	v_pk_fma_f32 v[166:167], v[36:37], v[36:37], v[166:167]
	v_pk_fma_f32 v[168:169], v[52:53], v[52:53], v[168:169]
	v_pk_fma_f32 v[170:171], v[68:69], v[68:69], v[170:171]
	v_pk_fma_f32 v[164:165], v[22:23], v[22:23], v[164:165]
	v_pk_fma_f32 v[166:167], v[38:39], v[38:39], v[166:167]
	v_pk_fma_f32 v[168:169], v[54:55], v[54:55], v[168:169]
	v_pk_fma_f32 v[170:171], v[70:71], v[70:71], v[170:171]
	v_pk_fma_f32 v[164:165], v[24:25], v[24:25], v[164:165]
	v_pk_fma_f32 v[166:167], v[40:41], v[40:41], v[166:167]
	v_pk_fma_f32 v[168:169], v[56:57], v[56:57], v[168:169]
	v_pk_fma_f32 v[170:171], v[72:73], v[72:73], v[170:171]
	v_pk_fma_f32 v[164:165], v[26:27], v[26:27], v[164:165]
	v_pk_fma_f32 v[166:167], v[42:43], v[42:43], v[166:167]
	v_pk_fma_f32 v[168:169], v[58:59], v[58:59], v[168:169]
	v_pk_fma_f32 v[170:171], v[74:75], v[74:75], v[170:171]
	v_pk_fma_f32 v[164:165], v[28:29], v[28:29], v[164:165]
	v_pk_fma_f32 v[166:167], v[44:45], v[44:45], v[166:167]
	v_pk_fma_f32 v[168:169], v[60:61], v[60:61], v[168:169]
	v_pk_fma_f32 v[170:171], v[76:77], v[76:77], v[170:171]
	v_pk_fma_f32 v[164:165], v[30:31], v[30:31], v[164:165]
	v_pk_fma_f32 v[166:167], v[46:47], v[46:47], v[166:167]
	v_pk_fma_f32 v[168:169], v[62:63], v[62:63], v[168:169]
	v_pk_fma_f32 v[170:171], v[78:79], v[78:79], v[170:171]
	v_add_f32_e32 v152, v164, v165
	v_add_f32_e32 v153, v166, v167
	v_add_f32_e32 v154, v168, v169
	v_add_f32_e32 v155, v170, v171
	s_lshl_b32 s7, s41, 11
	v_add_u32_e32 v150, s7, v145
	v_add_f32_dpp v156, v152, v152 quad_perm:[1,0,3,2] row_mask:0xf bank_mask:0xf
	v_add_f32_dpp v157, v153, v153 quad_perm:[1,0,3,2] row_mask:0xf bank_mask:0xf
	v_add_f32_dpp v158, v154, v154 quad_perm:[1,0,3,2] row_mask:0xf bank_mask:0xf
	v_add_f32_dpp v159, v155, v155 quad_perm:[1,0,3,2] row_mask:0xf bank_mask:0xf
	v_add_u32_e32 v151, 0x1000, v150
	v_add_f32_dpp v152, v156, v156 quad_perm:[2,3,0,1] row_mask:0xf bank_mask:0xf
	v_add_f32_dpp v153, v157, v157 quad_perm:[2,3,0,1] row_mask:0xf bank_mask:0xf
	v_add_f32_dpp v154, v158, v158 quad_perm:[2,3,0,1] row_mask:0xf bank_mask:0xf
	v_add_f32_dpp v155, v159, v159 quad_perm:[2,3,0,1] row_mask:0xf bank_mask:0xf
	s_nop 0
	v_add_f32_dpp v156, v152, v152 row_ror:4 row_mask:0xf bank_mask:0xf
	v_add_f32_dpp v157, v153, v153 row_ror:4 row_mask:0xf bank_mask:0xf
	v_add_f32_dpp v158, v154, v154 row_ror:4 row_mask:0xf bank_mask:0xf
	v_add_f32_dpp v159, v155, v155 row_ror:4 row_mask:0xf bank_mask:0xf
	s_nop 0
	v_add_f32_dpp v152, v156, v156 row_ror:8 row_mask:0xf bank_mask:0xf
	v_add_f32_dpp v153, v157, v157 row_ror:8 row_mask:0xf bank_mask:0xf
	v_add_f32_dpp v154, v158, v158 row_ror:8 row_mask:0xf bank_mask:0xf
	v_add_f32_dpp v155, v159, v159 row_ror:8 row_mask:0xf bank_mask:0xf
	ds_bpermute_b32 v156, v160, v152
	ds_bpermute_b32 v157, v160, v153
	ds_bpermute_b32 v158, v160, v154
	ds_bpermute_b32 v159, v160, v155
	s_waitcnt lgkmcnt(0)
	v_add_f32_e32 v152, v152, v156
	v_add_f32_e32 v153, v153, v157
	v_add_f32_e32 v154, v154, v158
	v_add_f32_e32 v155, v155, v159
	ds_bpermute_b32 v156, v161, v152
	ds_bpermute_b32 v157, v161, v153
	ds_bpermute_b32 v158, v161, v154
	ds_bpermute_b32 v159, v161, v155
	s_waitcnt lgkmcnt(0)
	v_add_f32_e32 v152, v152, v156
	v_add_f32_e32 v153, v153, v157
	v_add_f32_e32 v154, v154, v158
	v_add_f32_e32 v155, v155, v159
	v_fma_f32 v152, v152, s6, v174
	v_fma_f32 v153, v153, s6, v174
	v_fma_f32 v154, v154, s6, v174
	v_fma_f32 v155, v155, s6, v174
	v_rsq_f32_e32 v164, v152
	v_rsq_f32_e32 v166, v153
	v_rsq_f32_e32 v168, v154
	v_rsq_f32_e32 v170, v155
	v_pk_mul_f32 v[16:17], v[16:17], v[164:165] op_sel_hi:[1,0]
	v_pk_mul_f32 v[18:19], v[18:19], v[164:165] op_sel_hi:[1,0]
	v_pk_mul_f32 v[16:17], v[0:1], v[16:17]
	v_pk_mul_f32 v[18:19], v[2:3], v[18:19]
	v_cvt_pk_bf16_f32 v16, v16, v17
	v_cvt_pk_bf16_f32 v17, v18, v19
	global_store_dwordx2 v150, v[16:17], s[2:3] sc1
	v_pk_mul_f32 v[20:21], v[20:21], v[164:165] op_sel_hi:[1,0]
	v_pk_mul_f32 v[22:23], v[22:23], v[164:165] op_sel_hi:[1,0]
	v_pk_mul_f32 v[20:21], v[4:5], v[20:21]
	v_pk_mul_f32 v[22:23], v[6:7], v[22:23]
	v_cvt_pk_bf16_f32 v20, v20, v21
	v_cvt_pk_bf16_f32 v21, v22, v23
	global_store_dwordx2 v150, v[20:21], s[2:3] offset:512 sc1
	v_pk_mul_f32 v[24:25], v[24:25], v[164:165] op_sel_hi:[1,0]
	v_pk_mul_f32 v[26:27], v[26:27], v[164:165] op_sel_hi:[1,0]
	v_pk_mul_f32 v[24:25], v[8:9], v[24:25]
	v_pk_mul_f32 v[26:27], v[10:11], v[26:27]
	v_cvt_pk_bf16_f32 v24, v24, v25
	v_cvt_pk_bf16_f32 v25, v26, v27
	global_store_dwordx2 v150, v[24:25], s[2:3] offset:1024 sc1
	v_pk_mul_f32 v[28:29], v[28:29], v[164:165] op_sel_hi:[1,0]
	v_pk_mul_f32 v[30:31], v[30:31], v[164:165] op_sel_hi:[1,0]
	v_pk_mul_f32 v[28:29], v[12:13], v[28:29]
	v_pk_mul_f32 v[30:31], v[14:15], v[30:31]
	v_cvt_pk_bf16_f32 v28, v28, v29
	v_cvt_pk_bf16_f32 v29, v30, v31
	global_store_dwordx2 v150, v[28:29], s[2:3] offset:1536 sc1
	v_pk_mul_f32 v[32:33], v[32:33], v[166:167] op_sel_hi:[1,0]
	v_pk_mul_f32 v[34:35], v[34:35], v[166:167] op_sel_hi:[1,0]
	v_pk_mul_f32 v[32:33], v[0:1], v[32:33]
	v_pk_mul_f32 v[34:35], v[2:3], v[34:35]
	v_cvt_pk_bf16_f32 v32, v32, v33
	v_cvt_pk_bf16_f32 v33, v34, v35
	global_store_dwordx2 v150, v[32:33], s[2:3] offset:2048 sc1
	v_pk_mul_f32 v[36:37], v[36:37], v[166:167] op_sel_hi:[1,0]
	v_pk_mul_f32 v[38:39], v[38:39], v[166:167] op_sel_hi:[1,0]
	v_pk_mul_f32 v[36:37], v[4:5], v[36:37]
	v_pk_mul_f32 v[38:39], v[6:7], v[38:39]
	v_cvt_pk_bf16_f32 v36, v36, v37
	v_cvt_pk_bf16_f32 v37, v38, v39
	global_store_dwordx2 v150, v[36:37], s[2:3] offset:2560 sc1
	v_pk_mul_f32 v[40:41], v[40:41], v[166:167] op_sel_hi:[1,0]
	v_pk_mul_f32 v[42:43], v[42:43], v[166:167] op_sel_hi:[1,0]
	v_pk_mul_f32 v[40:41], v[8:9], v[40:41]
	v_pk_mul_f32 v[42:43], v[10:11], v[42:43]
	v_cvt_pk_bf16_f32 v40, v40, v41
	v_cvt_pk_bf16_f32 v41, v42, v43
	global_store_dwordx2 v150, v[40:41], s[2:3] offset:3072 sc1
	v_pk_mul_f32 v[44:45], v[44:45], v[166:167] op_sel_hi:[1,0]
	v_pk_mul_f32 v[46:47], v[46:47], v[166:167] op_sel_hi:[1,0]
	v_pk_mul_f32 v[44:45], v[12:13], v[44:45]
	v_pk_mul_f32 v[46:47], v[14:15], v[46:47]
	v_cvt_pk_bf16_f32 v44, v44, v45
	v_cvt_pk_bf16_f32 v45, v46, v47
	global_store_dwordx2 v150, v[44:45], s[2:3] offset:3584 sc1
	v_pk_mul_f32 v[48:49], v[48:49], v[168:169] op_sel_hi:[1,0]
	v_pk_mul_f32 v[50:51], v[50:51], v[168:169] op_sel_hi:[1,0]
	v_pk_mul_f32 v[48:49], v[0:1], v[48:49]
	v_pk_mul_f32 v[50:51], v[2:3], v[50:51]
	v_cvt_pk_bf16_f32 v48, v48, v49
	v_cvt_pk_bf16_f32 v49, v50, v51
	global_store_dwordx2 v151, v[48:49], s[2:3] sc1
	v_pk_mul_f32 v[52:53], v[52:53], v[168:169] op_sel_hi:[1,0]
	v_pk_mul_f32 v[54:55], v[54:55], v[168:169] op_sel_hi:[1,0]
	v_pk_mul_f32 v[52:53], v[4:5], v[52:53]
	v_pk_mul_f32 v[54:55], v[6:7], v[54:55]
	v_cvt_pk_bf16_f32 v52, v52, v53
	v_cvt_pk_bf16_f32 v53, v54, v55
	global_store_dwordx2 v151, v[52:53], s[2:3] offset:512 sc1
	v_pk_mul_f32 v[56:57], v[56:57], v[168:169] op_sel_hi:[1,0]
	v_pk_mul_f32 v[58:59], v[58:59], v[168:169] op_sel_hi:[1,0]
	v_pk_mul_f32 v[56:57], v[8:9], v[56:57]
	v_pk_mul_f32 v[58:59], v[10:11], v[58:59]
	v_cvt_pk_bf16_f32 v56, v56, v57
	v_cvt_pk_bf16_f32 v57, v58, v59
	global_store_dwordx2 v151, v[56:57], s[2:3] offset:1024 sc1
	v_pk_mul_f32 v[60:61], v[60:61], v[168:169] op_sel_hi:[1,0]
	v_pk_mul_f32 v[62:63], v[62:63], v[168:169] op_sel_hi:[1,0]
	v_pk_mul_f32 v[60:61], v[12:13], v[60:61]
	v_pk_mul_f32 v[62:63], v[14:15], v[62:63]
	v_cvt_pk_bf16_f32 v60, v60, v61
	v_cvt_pk_bf16_f32 v61, v62, v63
	global_store_dwordx2 v151, v[60:61], s[2:3] offset:1536 sc1
	v_pk_mul_f32 v[64:65], v[64:65], v[170:171] op_sel_hi:[1,0]
	v_pk_mul_f32 v[66:67], v[66:67], v[170:171] op_sel_hi:[1,0]
	v_pk_mul_f32 v[64:65], v[0:1], v[64:65]
	v_pk_mul_f32 v[66:67], v[2:3], v[66:67]
	v_cvt_pk_bf16_f32 v64, v64, v65
	v_cvt_pk_bf16_f32 v65, v66, v67
	global_store_dwordx2 v151, v[64:65], s[2:3] offset:2048 sc1
	v_pk_mul_f32 v[68:69], v[68:69], v[170:171] op_sel_hi:[1,0]
	v_pk_mul_f32 v[70:71], v[70:71], v[170:171] op_sel_hi:[1,0]
	v_pk_mul_f32 v[68:69], v[4:5], v[68:69]
	v_pk_mul_f32 v[70:71], v[6:7], v[70:71]
	v_cvt_pk_bf16_f32 v68, v68, v69
	v_cvt_pk_bf16_f32 v69, v70, v71
	global_store_dwordx2 v151, v[68:69], s[2:3] offset:2560 sc1
	v_pk_mul_f32 v[72:73], v[72:73], v[170:171] op_sel_hi:[1,0]
	v_pk_mul_f32 v[74:75], v[74:75], v[170:171] op_sel_hi:[1,0]
	v_pk_mul_f32 v[72:73], v[8:9], v[72:73]
	v_pk_mul_f32 v[74:75], v[10:11], v[74:75]
	v_cvt_pk_bf16_f32 v72, v72, v73
	v_cvt_pk_bf16_f32 v73, v74, v75
	global_store_dwordx2 v151, v[72:73], s[2:3] offset:3072 sc1
	v_pk_mul_f32 v[76:77], v[76:77], v[170:171] op_sel_hi:[1,0]
	v_pk_mul_f32 v[78:79], v[78:79], v[170:171] op_sel_hi:[1,0]
	v_pk_mul_f32 v[76:77], v[12:13], v[76:77]
	v_pk_mul_f32 v[78:79], v[14:15], v[78:79]
	v_cvt_pk_bf16_f32 v76, v76, v77
	v_cvt_pk_bf16_f32 v77, v78, v79
	global_store_dwordx2 v151, v[76:77], s[2:3] offset:3584 sc1
	s_mov_b32 s41, s32
	s_cmp_lt_i32 s41, 0x8000
	s_cbranch_scc0 .Lrn_done
.Lrn_step_B:
	s_add_i32 s32, s41, s43
	s_cmp_lt_i32 s32, 0x8000
	s_cbranch_scc0 .Lrn_nol_B
	s_lshl_b32 s7, s32, 12
	v_add_u32_e32 v146, s7, v144
	v_add_u32_e32 v147, 0x1000, v146
	v_add_u32_e32 v148, 0x2000, v146
	v_add_u32_e32 v149, 0x3000, v146
	global_load_dwordx4 v[16:19], v146, s[56:57] nt
	global_load_dwordx4 v[20:23], v146, s[56:57] offset:1024 nt
	global_load_dwordx4 v[24:27], v146, s[56:57] offset:2048 nt
	global_load_dwordx4 v[28:31], v146, s[56:57] offset:3072 nt
	global_load_dwordx4 v[32:35], v147, s[56:57] nt
	global_load_dwordx4 v[36:39], v147, s[56:57] offset:1024 nt
	global_load_dwordx4 v[40:43], v147, s[56:57] offset:2048 nt
	global_load_dwordx4 v[44:47], v147, s[56:57] offset:3072 nt
	global_load_dwordx4 v[48:51], v148, s[56:57] nt
	global_load_dwordx4 v[52:55], v148, s[56:57] offset:1024 nt
	global_load_dwordx4 v[56:59], v148, s[56:57] offset:2048 nt
	global_load_dwordx4 v[60:63], v148, s[56:57] offset:3072 nt
	global_load_dwordx4 v[64:67], v149, s[56:57] nt
	global_load_dwordx4 v[68:71], v149, s[56:57] offset:1024 nt
	global_load_dwordx4 v[72:75], v149, s[56:57] offset:2048 nt
	global_load_dwordx4 v[76:79], v149, s[56:57] offset:3072 nt
	s_waitcnt vmcnt(32)
	s_branch .Lrn_comp_B

.Lrn_comp_B:
	v_pk_mul_f32 v[164:165], v[80:81], v[80:81]
	v_pk_mul_f32 v[166:167], v[96:97], v[96:97]
	v_pk_mul_f32 v[168:169], v[112:113], v[112:113]
	v_pk_mul_f32 v[170:171], v[128:129], v[128:129]
	v_pk_fma_f32 v[164:165], v[82:83], v[82:83], v[164:165]
	v_pk_fma_f32 v[166:167], v[98:99], v[98:99], v[166:167]
	v_pk_fma_f32 v[168:169], v[114:115], v[114:115], v[168:169]
	v_pk_fma_f32 v[170:171], v[130:131], v[130:131], v[170:171]
	v_pk_fma_f32 v[164:165], v[84:85], v[84:85], v[164:165]
	v_pk_fma_f32 v[166:167], v[100:101], v[100:101], v[166:167]
	v_pk_fma_f32 v[168:169], v[116:117], v[116:117], v[168:169]
	v_pk_fma_f32 v[170:171], v[132:133], v[132:133], v[170:171]
	v_pk_fma_f32 v[164:165], v[86:87], v[86:87], v[164:165]
	v_pk_fma_f32 v[166:167], v[102:103], v[102:103], v[166:167]
	v_pk_fma_f32 v[168:169], v[118:119], v[118:119], v[168:169]
	v_pk_fma_f32 v[170:171], v[134:135], v[134:135], v[170:171]
	v_pk_fma_f32 v[164:165], v[88:89], v[88:89], v[164:165]
	v_pk_fma_f32 v[166:167], v[104:105], v[104:105], v[166:167]
	v_pk_fma_f32 v[168:169], v[120:121], v[120:121], v[168:169]
	v_pk_fma_f32 v[170:171], v[136:137], v[136:137], v[170:171]
	v_pk_fma_f32 v[164:165], v[90:91], v[90:91], v[164:165]
	v_pk_fma_f32 v[166:167], v[106:107], v[106:107], v[166:167]
	v_pk_fma_f32 v[168:169], v[122:123], v[122:123], v[168:169]
	v_pk_fma_f32 v[170:171], v[138:139], v[138:139], v[170:171]
	v_pk_fma_f32 v[164:165], v[92:93], v[92:93], v[164:165]
	v_pk_fma_f32 v[166:167], v[108:109], v[108:109], v[166:167]
	v_pk_fma_f32 v[168:169], v[124:125], v[124:125], v[168:169]
	v_pk_fma_f32 v[170:171], v[140:141], v[140:141], v[170:171]
	v_pk_fma_f32 v[164:165], v[94:95], v[94:95], v[164:165]
	v_pk_fma_f32 v[166:167], v[110:111], v[110:111], v[166:167]
	v_pk_fma_f32 v[168:169], v[126:127], v[126:127], v[168:169]
	v_pk_fma_f32 v[170:171], v[142:143], v[142:143], v[170:171]
	v_add_f32_e32 v152, v164, v165
	v_add_f32_e32 v153, v166, v167
	v_add_f32_e32 v154, v168, v169
	v_add_f32_e32 v155, v170, v171
	s_lshl_b32 s7, s41, 11
	v_add_u32_e32 v150, s7, v145
	v_add_f32_dpp v156, v152, v152 quad_perm:[1,0,3,2] row_mask:0xf bank_mask:0xf
	v_add_f32_dpp v157, v153, v153 quad_perm:[1,0,3,2] row_mask:0xf bank_mask:0xf
	v_add_f32_dpp v158, v154, v154 quad_perm:[1,0,3,2] row_mask:0xf bank_mask:0xf
	v_add_f32_dpp v159, v155, v155 quad_perm:[1,0,3,2] row_mask:0xf bank_mask:0xf
	v_add_u32_e32 v151, 0x1000, v150
	v_add_f32_dpp v152, v156, v156 quad_perm:[2,3,0,1] row_mask:0xf bank_mask:0xf
	v_add_f32_dpp v153, v157, v157 quad_perm:[2,3,0,1] row_mask:0xf bank_mask:0xf
	v_add_f32_dpp v154, v158, v158 quad_perm:[2,3,0,1] row_mask:0xf bank_mask:0xf
	v_add_f32_dpp v155, v159, v159 quad_perm:[2,3,0,1] row_mask:0xf bank_mask:0xf
	s_nop 0
	v_add_f32_dpp v156, v152, v152 row_ror:4 row_mask:0xf bank_mask:0xf
	v_add_f32_dpp v157, v153, v153 row_ror:4 row_mask:0xf bank_mask:0xf
	v_add_f32_dpp v158, v154, v154 row_ror:4 row_mask:0xf bank_mask:0xf
	v_add_f32_dpp v159, v155, v155 row_ror:4 row_mask:0xf bank_mask:0xf
	s_nop 0
	v_add_f32_dpp v152, v156, v156 row_ror:8 row_mask:0xf bank_mask:0xf
	v_add_f32_dpp v153, v157, v157 row_ror:8 row_mask:0xf bank_mask:0xf
	v_add_f32_dpp v154, v158, v158 row_ror:8 row_mask:0xf bank_mask:0xf
	v_add_f32_dpp v155, v159, v159 row_ror:8 row_mask:0xf bank_mask:0xf
	ds_bpermute_b32 v156, v160, v152
	ds_bpermute_b32 v157, v160, v153
	ds_bpermute_b32 v158, v160, v154
	ds_bpermute_b32 v159, v160, v155
	s_waitcnt lgkmcnt(0)
	v_add_f32_e32 v152, v152, v156
	v_add_f32_e32 v153, v153, v157
	v_add_f32_e32 v154, v154, v158
	v_add_f32_e32 v155, v155, v159
	ds_bpermute_b32 v156, v161, v152
	ds_bpermute_b32 v157, v161, v153
	ds_bpermute_b32 v158, v161, v154
	ds_bpermute_b32 v159, v161, v155
	s_waitcnt lgkmcnt(0)
	v_add_f32_e32 v152, v152, v156
	v_add_f32_e32 v153, v153, v157
	v_add_f32_e32 v154, v154, v158
	v_add_f32_e32 v155, v155, v159
	v_fma_f32 v152, v152, s6, v174
	v_fma_f32 v153, v153, s6, v174
	v_fma_f32 v154, v154, s6, v174
	v_fma_f32 v155, v155, s6, v174
	v_rsq_f32_e32 v164, v152
	v_rsq_f32_e32 v166, v153
	v_rsq_f32_e32 v168, v154
	v_rsq_f32_e32 v170, v155
	v_pk_mul_f32 v[80:81], v[80:81], v[164:165] op_sel_hi:[1,0]
	v_pk_mul_f32 v[82:83], v[82:83], v[164:165] op_sel_hi:[1,0]
	v_pk_mul_f32 v[80:81], v[0:1], v[80:81]
	v_pk_mul_f32 v[82:83], v[2:3], v[82:83]
	v_cvt_pk_bf16_f32 v80, v80, v81
	v_cvt_pk_bf16_f32 v81, v82, v83
	global_store_dwordx2 v150, v[80:81], s[2:3] sc1
	v_pk_mul_f32 v[84:85], v[84:85], v[164:165] op_sel_hi:[1,0]
	v_pk_mul_f32 v[86:87], v[86:87], v[164:165] op_sel_hi:[1,0]
	v_pk_mul_f32 v[84:85], v[4:5], v[84:85]
	v_pk_mul_f32 v[86:87], v[6:7], v[86:87]
	v_cvt_pk_bf16_f32 v84, v84, v85
	v_cvt_pk_bf16_f32 v85, v86, v87
	global_store_dwordx2 v150, v[84:85], s[2:3] offset:512 sc1
	v_pk_mul_f32 v[88:89], v[88:89], v[164:165] op_sel_hi:[1,0]
	v_pk_mul_f32 v[90:91], v[90:91], v[164:165] op_sel_hi:[1,0]
	v_pk_mul_f32 v[88:89], v[8:9], v[88:89]
	v_pk_mul_f32 v[90:91], v[10:11], v[90:91]
	v_cvt_pk_bf16_f32 v88, v88, v89
	v_cvt_pk_bf16_f32 v89, v90, v91
	global_store_dwordx2 v150, v[88:89], s[2:3] offset:1024 sc1
	v_pk_mul_f32 v[92:93], v[92:93], v[164:165] op_sel_hi:[1,0]
	v_pk_mul_f32 v[94:95], v[94:95], v[164:165] op_sel_hi:[1,0]
	v_pk_mul_f32 v[92:93], v[12:13], v[92:93]
	v_pk_mul_f32 v[94:95], v[14:15], v[94:95]
	v_cvt_pk_bf16_f32 v92, v92, v93
	v_cvt_pk_bf16_f32 v93, v94, v95
	global_store_dwordx2 v150, v[92:93], s[2:3] offset:1536 sc1
	v_pk_mul_f32 v[96:97], v[96:97], v[166:167] op_sel_hi:[1,0]
	v_pk_mul_f32 v[98:99], v[98:99], v[166:167] op_sel_hi:[1,0]
	v_pk_mul_f32 v[96:97], v[0:1], v[96:97]
	v_pk_mul_f32 v[98:99], v[2:3], v[98:99]
	v_cvt_pk_bf16_f32 v96, v96, v97
	v_cvt_pk_bf16_f32 v97, v98, v99
	global_store_dwordx2 v150, v[96:97], s[2:3] offset:2048 sc1
	v_pk_mul_f32 v[100:101], v[100:101], v[166:167] op_sel_hi:[1,0]
	v_pk_mul_f32 v[102:103], v[102:103], v[166:167] op_sel_hi:[1,0]
	v_pk_mul_f32 v[100:101], v[4:5], v[100:101]
	v_pk_mul_f32 v[102:103], v[6:7], v[102:103]
	v_cvt_pk_bf16_f32 v100, v100, v101
	v_cvt_pk_bf16_f32 v101, v102, v103
	global_store_dwordx2 v150, v[100:101], s[2:3] offset:2560 sc1
	v_pk_mul_f32 v[104:105], v[104:105], v[166:167] op_sel_hi:[1,0]
	v_pk_mul_f32 v[106:107], v[106:107], v[166:167] op_sel_hi:[1,0]
	v_pk_mul_f32 v[104:105], v[8:9], v[104:105]
	v_pk_mul_f32 v[106:107], v[10:11], v[106:107]
	v_cvt_pk_bf16_f32 v104, v104, v105
	v_cvt_pk_bf16_f32 v105, v106, v107
	global_store_dwordx2 v150, v[104:105], s[2:3] offset:3072 sc1
	v_pk_mul_f32 v[108:109], v[108:109], v[166:167] op_sel_hi:[1,0]
	v_pk_mul_f32 v[110:111], v[110:111], v[166:167] op_sel_hi:[1,0]
	v_pk_mul_f32 v[108:109], v[12:13], v[108:109]
	v_pk_mul_f32 v[110:111], v[14:15], v[110:111]
	v_cvt_pk_bf16_f32 v108, v108, v109
	v_cvt_pk_bf16_f32 v109, v110, v111
	global_store_dwordx2 v150, v[108:109], s[2:3] offset:3584 sc1
	v_pk_mul_f32 v[112:113], v[112:113], v[168:169] op_sel_hi:[1,0]
	v_pk_mul_f32 v[114:115], v[114:115], v[168:169] op_sel_hi:[1,0]
	v_pk_mul_f32 v[112:113], v[0:1], v[112:113]
	v_pk_mul_f32 v[114:115], v[2:3], v[114:115]
	v_cvt_pk_bf16_f32 v112, v112, v113
	v_cvt_pk_bf16_f32 v113, v114, v115
	global_store_dwordx2 v151, v[112:113], s[2:3] sc1
	v_pk_mul_f32 v[116:117], v[116:117], v[168:169] op_sel_hi:[1,0]
	v_pk_mul_f32 v[118:119], v[118:119], v[168:169] op_sel_hi:[1,0]
	v_pk_mul_f32 v[116:117], v[4:5], v[116:117]
	v_pk_mul_f32 v[118:119], v[6:7], v[118:119]
	v_cvt_pk_bf16_f32 v116, v116, v117
	v_cvt_pk_bf16_f32 v117, v118, v119
	global_store_dwordx2 v151, v[116:117], s[2:3] offset:512 sc1
	v_pk_mul_f32 v[120:121], v[120:121], v[168:169] op_sel_hi:[1,0]
	v_pk_mul_f32 v[122:123], v[122:123], v[168:169] op_sel_hi:[1,0]
	v_pk_mul_f32 v[120:121], v[8:9], v[120:121]
	v_pk_mul_f32 v[122:123], v[10:11], v[122:123]
	v_cvt_pk_bf16_f32 v120, v120, v121
	v_cvt_pk_bf16_f32 v121, v122, v123
	global_store_dwordx2 v151, v[120:121], s[2:3] offset:1024 sc1
	v_pk_mul_f32 v[124:125], v[124:125], v[168:169] op_sel_hi:[1,0]
	v_pk_mul_f32 v[126:127], v[126:127], v[168:169] op_sel_hi:[1,0]
	v_pk_mul_f32 v[124:125], v[12:13], v[124:125]
	v_pk_mul_f32 v[126:127], v[14:15], v[126:127]
	v_cvt_pk_bf16_f32 v124, v124, v125
	v_cvt_pk_bf16_f32 v125, v126, v127
	global_store_dwordx2 v151, v[124:125], s[2:3] offset:1536 sc1
	v_pk_mul_f32 v[128:129], v[128:129], v[170:171] op_sel_hi:[1,0]
	v_pk_mul_f32 v[130:131], v[130:131], v[170:171] op_sel_hi:[1,0]
	v_pk_mul_f32 v[128:129], v[0:1], v[128:129]
	v_pk_mul_f32 v[130:131], v[2:3], v[130:131]
	v_cvt_pk_bf16_f32 v128, v128, v129
	v_cvt_pk_bf16_f32 v129, v130, v131
	global_store_dwordx2 v151, v[128:129], s[2:3] offset:2048 sc1
	v_pk_mul_f32 v[132:133], v[132:133], v[170:171] op_sel_hi:[1,0]
	v_pk_mul_f32 v[134:135], v[134:135], v[170:171] op_sel_hi:[1,0]
	v_pk_mul_f32 v[132:133], v[4:5], v[132:133]
	v_pk_mul_f32 v[134:135], v[6:7], v[134:135]
	v_cvt_pk_bf16_f32 v132, v132, v133
	v_cvt_pk_bf16_f32 v133, v134, v135
	global_store_dwordx2 v151, v[132:133], s[2:3] offset:2560 sc1
	v_pk_mul_f32 v[136:137], v[136:137], v[170:171] op_sel_hi:[1,0]
	v_pk_mul_f32 v[138:139], v[138:139], v[170:171] op_sel_hi:[1,0]
	v_pk_mul_f32 v[136:137], v[8:9], v[136:137]
	v_pk_mul_f32 v[138:139], v[10:11], v[138:139]
	v_cvt_pk_bf16_f32 v136, v136, v137
	v_cvt_pk_bf16_f32 v137, v138, v139
	global_store_dwordx2 v151, v[136:137], s[2:3] offset:3072 sc1
	v_pk_mul_f32 v[140:141], v[140:141], v[170:171] op_sel_hi:[1,0]
	v_pk_mul_f32 v[142:143], v[142:143], v[170:171] op_sel_hi:[1,0]
	v_pk_mul_f32 v[140:141], v[12:13], v[140:141]
	v_pk_mul_f32 v[142:143], v[14:15], v[142:143]
	v_cvt_pk_bf16_f32 v140, v140, v141
	v_cvt_pk_bf16_f32 v141, v142, v143
	global_store_dwordx2 v151, v[140:141], s[2:3] offset:3584 sc1
	s_mov_b32 s41, s32
	s_cmp_lt_i32 s41, 0x8000
	s_cbranch_scc0 .Lrn_done
	s_branch .Lrn_step_A
